# strategy 9 (7.12 step 2): diff-attention serial tails shortened - row-max copy started before the row-sum adds (permlane wait states supplied by them), loop-head carry wait filled with the independent
# speedup vs baseline: 1.0010x; 1.0002x over previous
.LBB0_563:
	s_add_i32 s13, s12, -1
	s_min_u32 s34, s13, s4
	s_lshl_b64 s[30:31], s[34:35], 13
	v_lshl_add_u64 v[2:3], v[224:225], 0, s[30:31]
	global_load_dwordx4 v[196:199], v[2:3], off
	v_add_co_u32_e32 v2, vcc, s1, v218
	ds_read_b128 v[6:9], v243
	ds_read_b128 v[12:15], v242 offset:59392
	v_addc_co_u32_e32 v3, vcc, -1, v219, vcc
	global_load_dwordx4 v[200:203], v[2:3], off offset:-4096
	global_load_dwordx4 v[204:207], v[2:3], off
	ds_read_b128 v[2:5], v243 offset:4608
	s_waitcnt lgkmcnt(0)
	v_mfma_f32_32x32x16_bf16 v[160:175], v[6:9], v[12:15], v[96:111]
	ds_read_b128 v[112:115], v243 offset:32
	v_exp_f32_e32 v0, v128
	v_exp_f32_e32 v6, v129
	ds_read_b128 v[116:119], v242 offset:60416
	v_add_f32_e32 v11, v6, v0
	v_cvt_pk_bf16_f32 v10, v0, v6
	v_mfma_f32_32x32x16_bf16 v[144:159], v[2:5], v[12:15], v[96:111]
	ds_read_b128 v[6:9], v243 offset:4640
	v_exp_f32_e32 v0, v130
	v_exp_f32_e32 v120, v131
	v_add_f32_e32 v121, v0, v11
	v_cvt_pk_bf16_f32 v11, v0, v120
	v_add_f32_e32 v0, v120, v121
	s_waitcnt lgkmcnt(1)
	v_mfma_f32_32x32x16_bf16 v[160:175], v[112:115], v[116:119], v[160:175]
	ds_read_b128 v[2:5], v243 offset:64
	ds_read_b128 v[120:123], v242 offset:61440
	v_exp_f32_e32 v12, v132
	v_exp_f32_e32 v13, v133
	v_add_f32_e32 v0, v12, v0
	v_add_f32_e32 v0, v13, v0
	v_cvt_pk_bf16_f32 v12, v12, v13
	s_waitcnt lgkmcnt(2)
	v_mfma_f32_32x32x16_bf16 v[144:159], v[6:9], v[116:119], v[144:159]
	ds_read_b128 v[112:115], v243 offset:4672
	v_exp_f32_e32 v6, v134
	v_exp_f32_e32 v7, v135
	v_add_f32_e32 v0, v6, v0
	v_add_f32_e32 v0, v7, v0
	v_cvt_pk_bf16_f32 v13, v6, v7
	s_waitcnt lgkmcnt(1)
	v_mfma_f32_32x32x16_bf16 v[160:175], v[2:5], v[120:123], v[160:175]
	ds_read_b128 v[116:119], v243 offset:96
	ds_read_b128 v[124:127], v242 offset:62464
	v_exp_f32_e32 v2, v136
	v_exp_f32_e32 v3, v137
	v_add_f32_e32 v0, v2, v0
	v_add_f32_e32 v0, v3, v0
	v_cvt_pk_bf16_f32 v6, v2, v3
	s_waitcnt lgkmcnt(2)
	v_mfma_f32_32x32x16_bf16 v[144:159], v[112:115], v[120:123], v[144:159]
	ds_read_b128 v[2:5], v243 offset:4704
	v_exp_f32_e32 v7, v138
	v_exp_f32_e32 v8, v139
	v_add_f32_e32 v0, v7, v0
	v_add_f32_e32 v0, v8, v0
	v_cvt_pk_bf16_f32 v7, v7, v8
	s_waitcnt lgkmcnt(1)
	v_mfma_f32_32x32x16_bf16 v[160:175], v[116:119], v[124:127], v[160:175]
	ds_read_b64_tr_b16 v[112:113], v244 offset:18432
	ds_read_b64_tr_b16 v[114:115], v244 offset:20992
	v_exp_f32_e32 v8, v140
	v_exp_f32_e32 v9, v141
	v_add_f32_e32 v0, v8, v0
	v_add_f32_e32 v0, v9, v0
	v_cvt_pk_bf16_f32 v8, v8, v9
	s_waitcnt lgkmcnt(2)
	v_mfma_f32_32x32x16_bf16 v[144:159], v[2:5], v[124:127], v[144:159]
	ds_read_b64_tr_b16 v[116:117], v244 offset:18496
	ds_read_b64_tr_b16 v[118:119], v244 offset:21056
	v_exp_f32_e32 v9, v142
	v_exp_f32_e32 v14, v143
	v_add_f32_e32 v0, v9, v0
	v_add_f32_e32 v0, v14, v0
	v_cvt_pk_bf16_f32 v9, v9, v14
	s_waitcnt lgkmcnt(2)
	v_mfma_f32_32x32x16_bf16 v[64:79], v[112:115], v[188:191], v[64:79]
	ds_read_b64_tr_b16 v[120:121], v244 offset:18560
	ds_read_b64_tr_b16 v[122:123], v244 offset:21120
	v_exp_f32_e32 v2, v80
	v_max3_f32 v3, v160, s33, v144
	v_add_f32_e32 v0, v2, v0
	s_waitcnt lgkmcnt(2)
	v_mfma_f32_32x32x16_bf16 v[48:63], v[116:119], v[188:191], v[48:63]
	ds_read_b64_tr_b16 v[112:113], v244 offset:18624
	ds_read_b64_tr_b16 v[114:115], v244 offset:21184
	v_exp_f32_e32 v4, v81
	v_max3_f32 v3, v3, v161, v145
	v_add_f32_e32 v0, v4, v0
	v_cvt_pk_bf16_f32 v2, v2, v4
	s_waitcnt lgkmcnt(2)
	v_mfma_f32_32x32x16_bf16 v[32:47], v[120:123], v[188:191], v[32:47]
	ds_read_b64_tr_b16 v[116:117], v244 offset:23552
	ds_read_b64_tr_b16 v[118:119], v244 offset:26112
	v_exp_f32_e32 v4, v82
	v_max3_f32 v5, v3, v162, v146
	v_add_f32_e32 v0, v4, v0
	s_waitcnt lgkmcnt(2)
	v_mfma_f32_32x32x16_bf16 v[16:31], v[112:115], v[188:191], v[16:31]
	ds_read_b64_tr_b16 v[120:121], v244 offset:23616
	v_exp_f32_e32 v3, v83
	ds_read_b64_tr_b16 v[122:123], v244 offset:26176
	v_add_f32_e32 v0, v3, v0
	v_cvt_pk_bf16_f32 v3, v4, v3
	v_max3_f32 v4, v5, v163, v147
	s_waitcnt lgkmcnt(2)
	v_mfma_f32_32x32x16_bf16 v[64:79], v[116:119], v[184:187], v[64:79]
	ds_read_b64_tr_b16 v[80:81], v244 offset:23680
	ds_read_b64_tr_b16 v[82:83], v244 offset:26240
	v_exp_f32_e32 v5, v84
	v_max3_f32 v14, v4, v164, v148
	v_add_f32_e32 v0, v5, v0
	s_waitcnt lgkmcnt(2)
	v_mfma_f32_32x32x16_bf16 v[48:63], v[120:123], v[184:187], v[48:63]
	ds_read_b64_tr_b16 v[112:113], v244 offset:23744
	v_exp_f32_e32 v4, v85
	ds_read_b64_tr_b16 v[114:115], v244 offset:26304
	v_add_f32_e32 v0, v4, v0
	v_cvt_pk_bf16_f32 v4, v5, v4
	v_max3_f32 v5, v14, v165, v149
	s_waitcnt lgkmcnt(2)
	v_mfma_f32_32x32x16_bf16 v[32:47], v[80:83], v[184:187], v[32:47]
	ds_read_b64_tr_b16 v[116:117], v244 offset:28672
	ds_read_b64_tr_b16 v[118:119], v244 offset:31232
	v_exp_f32_e32 v14, v86
	v_max3_f32 v15, v5, v166, v150
	v_add_f32_e32 v0, v14, v0
	s_waitcnt lgkmcnt(2)
	v_mfma_f32_32x32x16_bf16 v[16:31], v[112:115], v[184:187], v[16:31]
	ds_read_b64_tr_b16 v[80:81], v244 offset:28736
	v_exp_f32_e32 v5, v87
	ds_read_b64_tr_b16 v[82:83], v244 offset:31296
	v_add_f32_e32 v0, v5, v0
	v_cvt_pk_bf16_f32 v5, v14, v5
	v_max3_f32 v14, v15, v167, v151
	s_waitcnt lgkmcnt(2)
	v_mfma_f32_32x32x16_bf16 v[64:79], v[116:119], v[176:179], v[64:79]
	ds_read_b64_tr_b16 v[84:85], v244 offset:28800
	ds_read_b64_tr_b16 v[86:87], v244 offset:31360
	v_exp_f32_e32 v15, v88
	v_max3_f32 v14, v14, v168, v152
	v_add_f32_e32 v0, v15, v0
	s_waitcnt lgkmcnt(2)
	v_mfma_f32_32x32x16_bf16 v[48:63], v[80:83], v[176:179], v[48:63]
	ds_read_b64_tr_b16 v[112:113], v244 offset:28864
	ds_read_b64_tr_b16 v[114:115], v244 offset:31424
	v_exp_f32_e32 v80, v89
	v_max3_f32 v14, v14, v169, v153
	v_add_f32_e32 v0, v80, v0
	v_cvt_pk_bf16_f32 v192, v15, v80
	s_waitcnt lgkmcnt(2)
	v_mfma_f32_32x32x16_bf16 v[32:47], v[84:87], v[176:179], v[32:47]
	ds_read_b64_tr_b16 v[80:81], v244 offset:33792
	ds_read_b64_tr_b16 v[82:83], v244 offset:36352
	v_exp_f32_e32 v15, v90
	v_max3_f32 v14, v14, v170, v154
	v_add_f32_e32 v0, v15, v0
	s_waitcnt lgkmcnt(2)
	v_mfma_f32_32x32x16_bf16 v[16:31], v[112:115], v[176:179], v[16:31]
	ds_read_b64_tr_b16 v[84:85], v244 offset:33856
	ds_read_b64_tr_b16 v[86:87], v244 offset:36416
	v_exp_f32_e32 v88, v91
	v_max3_f32 v14, v14, v171, v155
	v_add_f32_e32 v0, v88, v0
	v_cvt_pk_bf16_f32 v193, v15, v88
	s_waitcnt lgkmcnt(2)
	v_mfma_f32_32x32x16_bf16 v[64:79], v[80:83], v[180:183], v[64:79]
	ds_read_b64_tr_b16 v[88:89], v244 offset:33920
	ds_read_b64_tr_b16 v[90:91], v244 offset:36480
	v_exp_f32_e32 v15, v92
	v_max3_f32 v14, v14, v172, v156
	v_add_f32_e32 v0, v15, v0
	s_waitcnt lgkmcnt(2)
	v_mfma_f32_32x32x16_bf16 v[48:63], v[84:87], v[180:183], v[48:63]
	ds_read_b64_tr_b16 v[80:81], v244 offset:33984
	ds_read_b64_tr_b16 v[82:83], v244 offset:36544
	v_exp_f32_e32 v84, v93
	v_max3_f32 v14, v14, v173, v157
	v_add_f32_e32 v0, v84, v0
	v_cvt_pk_bf16_f32 v194, v15, v84
	s_waitcnt lgkmcnt(2)
	v_mfma_f32_32x32x16_bf16 v[32:47], v[88:91], v[180:183], v[32:47]
	v_exp_f32_e32 v15, v94
	v_max3_f32 v14, v14, v174, v158
	v_add_f32_e32 v0, v15, v0
	s_waitcnt lgkmcnt(0)
	v_mfma_f32_32x32x16_bf16 v[16:31], v[80:83], v[180:183], v[16:31]
	v_exp_f32_e32 v80, v95
	s_nop 0
	v_add_f32_e32 v0, v80, v0
	v_cvt_pk_bf16_f32 v195, v15, v80
	v_max3_f32 v15, v14, v175, v159
	v_mov_b32_e32 v14, v0
	v_cmp_gt_f32_e32 vcc, 1.0, v226
	s_nop 0
	v_permlane32_swap_b32_e32 v0, v14
	s_cbranch_vccz .LBB0_565
	v_pk_mul_f32 v[78:79], v[226:227], v[78:79] op_sel_hi:[0,1]
	v_pk_mul_f32 v[76:77], v[226:227], v[76:77] op_sel_hi:[0,1]
	v_pk_mul_f32 v[74:75], v[226:227], v[74:75] op_sel_hi:[0,1]
	v_pk_mul_f32 v[72:73], v[226:227], v[72:73] op_sel_hi:[0,1]
	v_pk_mul_f32 v[70:71], v[226:227], v[70:71] op_sel_hi:[0,1]
	v_pk_mul_f32 v[68:69], v[226:227], v[68:69] op_sel_hi:[0,1]
	v_pk_mul_f32 v[66:67], v[226:227], v[66:67] op_sel_hi:[0,1]
	v_pk_mul_f32 v[64:65], v[226:227], v[64:65] op_sel_hi:[0,1]
	v_pk_mul_f32 v[62:63], v[226:227], v[62:63] op_sel_hi:[0,1]
	v_pk_mul_f32 v[60:61], v[226:227], v[60:61] op_sel_hi:[0,1]
	v_pk_mul_f32 v[58:59], v[226:227], v[58:59] op_sel_hi:[0,1]
	v_pk_mul_f32 v[56:57], v[226:227], v[56:57] op_sel_hi:[0,1]
	v_pk_mul_f32 v[54:55], v[226:227], v[54:55] op_sel_hi:[0,1]
	v_pk_mul_f32 v[52:53], v[226:227], v[52:53] op_sel_hi:[0,1]
	v_pk_mul_f32 v[50:51], v[226:227], v[50:51] op_sel_hi:[0,1]
	v_pk_mul_f32 v[48:49], v[226:227], v[48:49] op_sel_hi:[0,1]
	v_pk_mul_f32 v[46:47], v[226:227], v[46:47] op_sel_hi:[0,1]
	v_pk_mul_f32 v[44:45], v[226:227], v[44:45] op_sel_hi:[0,1]
	v_pk_mul_f32 v[42:43], v[226:227], v[42:43] op_sel_hi:[0,1]
	v_pk_mul_f32 v[40:41], v[226:227], v[40:41] op_sel_hi:[0,1]
	v_pk_mul_f32 v[38:39], v[226:227], v[38:39] op_sel_hi:[0,1]
	v_pk_mul_f32 v[36:37], v[226:227], v[36:37] op_sel_hi:[0,1]
	v_pk_mul_f32 v[34:35], v[226:227], v[34:35] op_sel_hi:[0,1]
	v_pk_mul_f32 v[32:33], v[226:227], v[32:33] op_sel_hi:[0,1]
	v_pk_mul_f32 v[30:31], v[226:227], v[30:31] op_sel_hi:[0,1]
	v_pk_mul_f32 v[28:29], v[226:227], v[28:29] op_sel_hi:[0,1]
	v_pk_mul_f32 v[26:27], v[226:227], v[26:27] op_sel_hi:[0,1]
	v_pk_mul_f32 v[24:25], v[226:227], v[24:25] op_sel_hi:[0,1]
	v_pk_mul_f32 v[22:23], v[226:227], v[22:23] op_sel_hi:[0,1]
	v_pk_mul_f32 v[20:21], v[226:227], v[20:21] op_sel_hi:[0,1]
	v_pk_mul_f32 v[18:19], v[226:227], v[18:19] op_sel_hi:[0,1]
	v_pk_mul_f32 v[16:17], v[226:227], v[16:17] op_sel_hi:[0,1]
.LBB0_565:
	v_mov_b32_e32 v238, v15
	v_add_f32_e32 v0, v0, v14
	v_add_f32_e32 v14, v248, v0
	v_permlane32_swap_b32_e32 v15, v238
	v_max_f32_e32 v0, v238, v238
	v_max_f32_e32 v15, v15, v15
	v_max_f32_e32 v0, v15, v0
	v_cmp_lt_f32_e32 vcc, s28, v0
	s_cbranch_vccz .LBB0_567
	v_max_f32_e32 v0, v0, v0
	v_max_f32_e32 v80, 0, v0
	v_exp_f32_e64 v0, -v80
	v_add_f32_e32 v247, v247, v80
	v_xor_b32_e32 v112, 0x80000000, v247
	v_pk_add_f32 v[160:161], v[160:161], v[80:81] op_sel_hi:[1,0] neg_lo:[0,1] neg_hi:[0,1]
	v_pk_add_f32 v[144:145], v[144:145], v[80:81] op_sel_hi:[1,0] neg_lo:[0,1] neg_hi:[0,1]
	v_pk_add_f32 v[162:163], v[162:163], v[80:81] op_sel_hi:[1,0] neg_lo:[0,1] neg_hi:[0,1]
	v_pk_add_f32 v[146:147], v[146:147], v[80:81] op_sel_hi:[1,0] neg_lo:[0,1] neg_hi:[0,1]
	v_pk_add_f32 v[164:165], v[164:165], v[80:81] op_sel_hi:[1,0] neg_lo:[0,1] neg_hi:[0,1]
	v_pk_add_f32 v[148:149], v[148:149], v[80:81] op_sel_hi:[1,0] neg_lo:[0,1] neg_hi:[0,1]
	v_pk_add_f32 v[166:167], v[166:167], v[80:81] op_sel_hi:[1,0] neg_lo:[0,1] neg_hi:[0,1]
	v_pk_add_f32 v[150:151], v[150:151], v[80:81] op_sel_hi:[1,0] neg_lo:[0,1] neg_hi:[0,1]
	v_pk_add_f32 v[168:169], v[168:169], v[80:81] op_sel_hi:[1,0] neg_lo:[0,1] neg_hi:[0,1]
	v_pk_add_f32 v[152:153], v[152:153], v[80:81] op_sel_hi:[1,0] neg_lo:[0,1] neg_hi:[0,1]
	v_pk_add_f32 v[170:171], v[170:171], v[80:81] op_sel_hi:[1,0] neg_lo:[0,1] neg_hi:[0,1]
	v_pk_add_f32 v[154:155], v[154:155], v[80:81] op_sel_hi:[1,0] neg_lo:[0,1] neg_hi:[0,1]
	v_pk_add_f32 v[172:173], v[172:173], v[80:81] op_sel_hi:[1,0] neg_lo:[0,1] neg_hi:[0,1]
	v_pk_add_f32 v[156:157], v[156:157], v[80:81] op_sel_hi:[1,0] neg_lo:[0,1] neg_hi:[0,1]
	v_pk_add_f32 v[174:175], v[174:175], v[80:81] op_sel_hi:[1,0] neg_lo:[0,1] neg_hi:[0,1]
	v_pk_add_f32 v[158:159], v[158:159], v[80:81] op_sel_hi:[1,0] neg_lo:[0,1] neg_hi:[0,1]
	v_mul_f32_e32 v14, v14, v0
	v_mov_b32_e32 v113, v112
	v_mov_b32_e32 v114, v112
	v_mov_b32_e32 v115, v112
	v_mov_b32_e32 v116, v112
	v_mov_b32_e32 v117, v112
	v_mov_b32_e32 v118, v112
	v_mov_b32_e32 v119, v112
	v_mov_b32_e32 v120, v112
	v_mov_b32_e32 v121, v112
	v_mov_b32_e32 v122, v112
	v_mov_b32_e32 v123, v112
	v_mov_b32_e32 v124, v112
	v_mov_b32_e32 v125, v112
	v_mov_b32_e32 v126, v112
	v_mov_b32_e32 v127, v112
	v_mov_b32_e32 v96, v112
	v_mov_b32_e32 v97, v112
	v_mov_b32_e32 v98, v112
	v_mov_b32_e32 v99, v112
	v_mov_b32_e32 v100, v112
	v_mov_b32_e32 v101, v112
	v_mov_b32_e32 v102, v112
	v_mov_b32_e32 v103, v112
	v_mov_b32_e32 v104, v112
	v_mov_b32_e32 v105, v112
	v_mov_b32_e32 v106, v112
	v_mov_b32_e32 v107, v112
	v_mov_b32_e32 v108, v112
	v_mov_b32_e32 v109, v112
	v_mov_b32_e32 v110, v112
	v_mov_b32_e32 v111, v112
	s_branch .LBB0_568

.LBB0_582:
	s_add_i32 s13, s12, -1
	s_min_u32 s34, s13, s4
	s_lshl_b64 s[30:31], s[34:35], 13
	v_lshl_add_u64 v[2:3], v[216:217], 0, s[30:31]
	global_load_dwordx4 v[196:199], v[2:3], off
	v_add_co_u32_e32 v2, vcc, s1, v212
	ds_read_b128 v[6:9], v243
	ds_read_b128 v[12:15], v242 offset:59392
	v_addc_co_u32_e32 v3, vcc, -1, v213, vcc
	global_load_dwordx4 v[200:203], v[2:3], off offset:-4096
	global_load_dwordx4 v[204:207], v[2:3], off
	ds_read_b128 v[2:5], v243 offset:4608
	s_waitcnt lgkmcnt(0)
	v_mfma_f32_32x32x16_bf16 v[160:175], v[6:9], v[12:15], v[96:111]
	ds_read_b128 v[112:115], v243 offset:32
	v_exp_f32_e32 v0, v128
	v_exp_f32_e32 v6, v129
	ds_read_b128 v[116:119], v242 offset:60416
	v_add_f32_e32 v11, v6, v0
	v_cvt_pk_bf16_f32 v10, v0, v6
	v_mfma_f32_32x32x16_bf16 v[144:159], v[2:5], v[12:15], v[96:111]
	ds_read_b128 v[6:9], v243 offset:4640
	v_exp_f32_e32 v0, v130
	v_exp_f32_e32 v120, v131
	v_add_f32_e32 v121, v0, v11
	v_cvt_pk_bf16_f32 v11, v0, v120
	v_add_f32_e32 v0, v120, v121
	s_waitcnt lgkmcnt(1)
	v_mfma_f32_32x32x16_bf16 v[160:175], v[112:115], v[116:119], v[160:175]
	ds_read_b128 v[2:5], v243 offset:64
	ds_read_b128 v[120:123], v242 offset:61440
	v_exp_f32_e32 v12, v132
	v_exp_f32_e32 v13, v133
	v_add_f32_e32 v0, v12, v0
	v_add_f32_e32 v0, v13, v0
	v_cvt_pk_bf16_f32 v12, v12, v13
	s_waitcnt lgkmcnt(2)
	v_mfma_f32_32x32x16_bf16 v[144:159], v[6:9], v[116:119], v[144:159]
	ds_read_b128 v[112:115], v243 offset:4672
	v_exp_f32_e32 v6, v134
	v_exp_f32_e32 v7, v135
	v_add_f32_e32 v0, v6, v0
	v_add_f32_e32 v0, v7, v0
	v_cvt_pk_bf16_f32 v13, v6, v7
	s_waitcnt lgkmcnt(1)
	v_mfma_f32_32x32x16_bf16 v[160:175], v[2:5], v[120:123], v[160:175]
	ds_read_b128 v[116:119], v243 offset:96
	ds_read_b128 v[124:127], v242 offset:62464
	v_exp_f32_e32 v2, v136
	v_exp_f32_e32 v3, v137
	v_add_f32_e32 v0, v2, v0
	v_add_f32_e32 v0, v3, v0
	v_cvt_pk_bf16_f32 v6, v2, v3
	s_waitcnt lgkmcnt(2)
	v_mfma_f32_32x32x16_bf16 v[144:159], v[112:115], v[120:123], v[144:159]
	ds_read_b128 v[2:5], v243 offset:4704
	v_exp_f32_e32 v7, v138
	v_exp_f32_e32 v8, v139
	v_add_f32_e32 v0, v7, v0
	v_add_f32_e32 v0, v8, v0
	v_cvt_pk_bf16_f32 v7, v7, v8
	s_waitcnt lgkmcnt(1)
	v_mfma_f32_32x32x16_bf16 v[160:175], v[116:119], v[124:127], v[160:175]
	ds_read_b64_tr_b16 v[112:113], v244 offset:18432
	ds_read_b64_tr_b16 v[114:115], v244 offset:20992
	v_exp_f32_e32 v8, v140
	v_exp_f32_e32 v9, v141
	v_add_f32_e32 v0, v8, v0
	v_add_f32_e32 v0, v9, v0
	v_cvt_pk_bf16_f32 v8, v8, v9
	s_waitcnt lgkmcnt(2)
	v_mfma_f32_32x32x16_bf16 v[144:159], v[2:5], v[124:127], v[144:159]
	ds_read_b64_tr_b16 v[116:117], v244 offset:18496
	ds_read_b64_tr_b16 v[118:119], v244 offset:21056
	v_exp_f32_e32 v9, v142
	v_exp_f32_e32 v14, v143
	v_add_f32_e32 v0, v9, v0
	v_add_f32_e32 v0, v14, v0
	v_cvt_pk_bf16_f32 v9, v9, v14
	s_waitcnt lgkmcnt(2)
	v_mfma_f32_32x32x16_bf16 v[64:79], v[112:115], v[188:191], v[64:79]
	ds_read_b64_tr_b16 v[120:121], v244 offset:18560
	ds_read_b64_tr_b16 v[122:123], v244 offset:21120
	v_exp_f32_e32 v2, v80
	v_max3_f32 v3, v160, s33, v144
	v_add_f32_e32 v0, v2, v0
	s_waitcnt lgkmcnt(2)
	v_mfma_f32_32x32x16_bf16 v[48:63], v[116:119], v[188:191], v[48:63]
	ds_read_b64_tr_b16 v[112:113], v244 offset:18624
	ds_read_b64_tr_b16 v[114:115], v244 offset:21184
	v_exp_f32_e32 v4, v81
	v_max3_f32 v3, v3, v161, v145
	v_add_f32_e32 v0, v4, v0
	v_cvt_pk_bf16_f32 v2, v2, v4
	s_waitcnt lgkmcnt(2)
	v_mfma_f32_32x32x16_bf16 v[32:47], v[120:123], v[188:191], v[32:47]
	ds_read_b64_tr_b16 v[116:117], v244 offset:23552
	ds_read_b64_tr_b16 v[118:119], v244 offset:26112
	v_exp_f32_e32 v4, v82
	v_max3_f32 v5, v3, v162, v146
	v_add_f32_e32 v0, v4, v0
	s_waitcnt lgkmcnt(2)
	v_mfma_f32_32x32x16_bf16 v[16:31], v[112:115], v[188:191], v[16:31]
	ds_read_b64_tr_b16 v[120:121], v244 offset:23616
	v_exp_f32_e32 v3, v83
	ds_read_b64_tr_b16 v[122:123], v244 offset:26176
	v_add_f32_e32 v0, v3, v0
	v_cvt_pk_bf16_f32 v3, v4, v3
	v_max3_f32 v4, v5, v163, v147
	s_waitcnt lgkmcnt(2)
	v_mfma_f32_32x32x16_bf16 v[64:79], v[116:119], v[184:187], v[64:79]
	ds_read_b64_tr_b16 v[80:81], v244 offset:23680
	ds_read_b64_tr_b16 v[82:83], v244 offset:26240
	v_exp_f32_e32 v5, v84
	v_max3_f32 v14, v4, v164, v148
	v_add_f32_e32 v0, v5, v0
	s_waitcnt lgkmcnt(2)
	v_mfma_f32_32x32x16_bf16 v[48:63], v[120:123], v[184:187], v[48:63]
	ds_read_b64_tr_b16 v[112:113], v244 offset:23744
	v_exp_f32_e32 v4, v85
	ds_read_b64_tr_b16 v[114:115], v244 offset:26304
	v_add_f32_e32 v0, v4, v0
	v_cvt_pk_bf16_f32 v4, v5, v4
	v_max3_f32 v5, v14, v165, v149
	s_waitcnt lgkmcnt(2)
	v_mfma_f32_32x32x16_bf16 v[32:47], v[80:83], v[184:187], v[32:47]
	ds_read_b64_tr_b16 v[116:117], v244 offset:28672
	ds_read_b64_tr_b16 v[118:119], v244 offset:31232
	v_exp_f32_e32 v14, v86
	v_max3_f32 v15, v5, v166, v150
	v_add_f32_e32 v0, v14, v0
	s_waitcnt lgkmcnt(2)
	v_mfma_f32_32x32x16_bf16 v[16:31], v[112:115], v[184:187], v[16:31]
	ds_read_b64_tr_b16 v[80:81], v244 offset:28736
	v_exp_f32_e32 v5, v87
	ds_read_b64_tr_b16 v[82:83], v244 offset:31296
	v_add_f32_e32 v0, v5, v0
	v_cvt_pk_bf16_f32 v5, v14, v5
	v_max3_f32 v14, v15, v167, v151
	s_waitcnt lgkmcnt(2)
	v_mfma_f32_32x32x16_bf16 v[64:79], v[116:119], v[176:179], v[64:79]
	ds_read_b64_tr_b16 v[84:85], v244 offset:28800
	ds_read_b64_tr_b16 v[86:87], v244 offset:31360
	v_exp_f32_e32 v15, v88
	v_max3_f32 v14, v14, v168, v152
	v_add_f32_e32 v0, v15, v0
	s_waitcnt lgkmcnt(2)
	v_mfma_f32_32x32x16_bf16 v[48:63], v[80:83], v[176:179], v[48:63]
	ds_read_b64_tr_b16 v[112:113], v244 offset:28864
	ds_read_b64_tr_b16 v[114:115], v244 offset:31424
	v_exp_f32_e32 v80, v89
	v_max3_f32 v14, v14, v169, v153
	v_add_f32_e32 v0, v80, v0
	v_cvt_pk_bf16_f32 v192, v15, v80
	s_waitcnt lgkmcnt(2)
	v_mfma_f32_32x32x16_bf16 v[32:47], v[84:87], v[176:179], v[32:47]
	ds_read_b64_tr_b16 v[80:81], v244 offset:33792
	ds_read_b64_tr_b16 v[82:83], v244 offset:36352
	v_exp_f32_e32 v15, v90
	v_max3_f32 v14, v14, v170, v154
	v_add_f32_e32 v0, v15, v0
	s_waitcnt lgkmcnt(2)
	v_mfma_f32_32x32x16_bf16 v[16:31], v[112:115], v[176:179], v[16:31]
	ds_read_b64_tr_b16 v[84:85], v244 offset:33856
	ds_read_b64_tr_b16 v[86:87], v244 offset:36416
	v_exp_f32_e32 v88, v91
	v_max3_f32 v14, v14, v171, v155
	v_add_f32_e32 v0, v88, v0
	v_cvt_pk_bf16_f32 v193, v15, v88
	s_waitcnt lgkmcnt(2)
	v_mfma_f32_32x32x16_bf16 v[64:79], v[80:83], v[180:183], v[64:79]
	ds_read_b64_tr_b16 v[88:89], v244 offset:33920
	ds_read_b64_tr_b16 v[90:91], v244 offset:36480
	v_exp_f32_e32 v15, v92
	v_max3_f32 v14, v14, v172, v156
	v_add_f32_e32 v0, v15, v0
	s_waitcnt lgkmcnt(2)
	v_mfma_f32_32x32x16_bf16 v[48:63], v[84:87], v[180:183], v[48:63]
	ds_read_b64_tr_b16 v[80:81], v244 offset:33984
	ds_read_b64_tr_b16 v[82:83], v244 offset:36544
	v_exp_f32_e32 v84, v93
	v_max3_f32 v14, v14, v173, v157
	v_add_f32_e32 v0, v84, v0
	v_cvt_pk_bf16_f32 v194, v15, v84
	s_waitcnt lgkmcnt(2)
	v_mfma_f32_32x32x16_bf16 v[32:47], v[88:91], v[180:183], v[32:47]
	v_exp_f32_e32 v15, v94
	v_max3_f32 v14, v14, v174, v158
	v_add_f32_e32 v0, v15, v0
	s_waitcnt lgkmcnt(0)
	v_mfma_f32_32x32x16_bf16 v[16:31], v[80:83], v[180:183], v[16:31]
	v_exp_f32_e32 v80, v95
	s_nop 0
	v_add_f32_e32 v0, v80, v0
	v_cvt_pk_bf16_f32 v195, v15, v80
	v_max3_f32 v15, v14, v175, v159
	v_mov_b32_e32 v14, v0
	v_cmp_gt_f32_e32 vcc, 1.0, v220
	s_nop 0
	v_permlane32_swap_b32_e32 v0, v14
	s_cbranch_vccz .LBB0_584
	v_pk_mul_f32 v[78:79], v[220:221], v[78:79] op_sel_hi:[0,1]
	v_pk_mul_f32 v[76:77], v[220:221], v[76:77] op_sel_hi:[0,1]
	v_pk_mul_f32 v[74:75], v[220:221], v[74:75] op_sel_hi:[0,1]
	v_pk_mul_f32 v[72:73], v[220:221], v[72:73] op_sel_hi:[0,1]
	v_pk_mul_f32 v[70:71], v[220:221], v[70:71] op_sel_hi:[0,1]
	v_pk_mul_f32 v[68:69], v[220:221], v[68:69] op_sel_hi:[0,1]
	v_pk_mul_f32 v[66:67], v[220:221], v[66:67] op_sel_hi:[0,1]
	v_pk_mul_f32 v[64:65], v[220:221], v[64:65] op_sel_hi:[0,1]
	v_pk_mul_f32 v[62:63], v[220:221], v[62:63] op_sel_hi:[0,1]
	v_pk_mul_f32 v[60:61], v[220:221], v[60:61] op_sel_hi:[0,1]
	v_pk_mul_f32 v[58:59], v[220:221], v[58:59] op_sel_hi:[0,1]
	v_pk_mul_f32 v[56:57], v[220:221], v[56:57] op_sel_hi:[0,1]
	v_pk_mul_f32 v[54:55], v[220:221], v[54:55] op_sel_hi:[0,1]
	v_pk_mul_f32 v[52:53], v[220:221], v[52:53] op_sel_hi:[0,1]
	v_pk_mul_f32 v[50:51], v[220:221], v[50:51] op_sel_hi:[0,1]
	v_pk_mul_f32 v[48:49], v[220:221], v[48:49] op_sel_hi:[0,1]
	v_pk_mul_f32 v[46:47], v[220:221], v[46:47] op_sel_hi:[0,1]
	v_pk_mul_f32 v[44:45], v[220:221], v[44:45] op_sel_hi:[0,1]
	v_pk_mul_f32 v[42:43], v[220:221], v[42:43] op_sel_hi:[0,1]
	v_pk_mul_f32 v[40:41], v[220:221], v[40:41] op_sel_hi:[0,1]
	v_pk_mul_f32 v[38:39], v[220:221], v[38:39] op_sel_hi:[0,1]
	v_pk_mul_f32 v[36:37], v[220:221], v[36:37] op_sel_hi:[0,1]
	v_pk_mul_f32 v[34:35], v[220:221], v[34:35] op_sel_hi:[0,1]
	v_pk_mul_f32 v[32:33], v[220:221], v[32:33] op_sel_hi:[0,1]
	v_pk_mul_f32 v[30:31], v[220:221], v[30:31] op_sel_hi:[0,1]
	v_pk_mul_f32 v[28:29], v[220:221], v[28:29] op_sel_hi:[0,1]
	v_pk_mul_f32 v[26:27], v[220:221], v[26:27] op_sel_hi:[0,1]
	v_pk_mul_f32 v[24:25], v[220:221], v[24:25] op_sel_hi:[0,1]
	v_pk_mul_f32 v[22:23], v[220:221], v[22:23] op_sel_hi:[0,1]
	v_pk_mul_f32 v[20:21], v[220:221], v[20:21] op_sel_hi:[0,1]
	v_pk_mul_f32 v[18:19], v[220:221], v[18:19] op_sel_hi:[0,1]
	v_pk_mul_f32 v[16:17], v[220:221], v[16:17] op_sel_hi:[0,1]
.LBB0_584:
	v_mov_b32_e32 v238, v15
	v_add_f32_e32 v0, v0, v14
	v_add_f32_e32 v14, v222, v0
	v_permlane32_swap_b32_e32 v15, v238
	v_max_f32_e32 v0, v238, v238
	v_max_f32_e32 v15, v15, v15
	v_max_f32_e32 v0, v15, v0
	v_cmp_lt_f32_e32 vcc, s28, v0
	s_cbranch_vccz .LBB0_586
	v_max_f32_e32 v0, v0, v0
	v_max_f32_e32 v80, 0, v0
	v_exp_f32_e64 v0, -v80
	v_add_f32_e32 v221, v221, v80
	v_xor_b32_e32 v112, 0x80000000, v221
	v_pk_add_f32 v[160:161], v[160:161], v[80:81] op_sel_hi:[1,0] neg_lo:[0,1] neg_hi:[0,1]
	v_pk_add_f32 v[144:145], v[144:145], v[80:81] op_sel_hi:[1,0] neg_lo:[0,1] neg_hi:[0,1]
	v_pk_add_f32 v[162:163], v[162:163], v[80:81] op_sel_hi:[1,0] neg_lo:[0,1] neg_hi:[0,1]
	v_pk_add_f32 v[146:147], v[146:147], v[80:81] op_sel_hi:[1,0] neg_lo:[0,1] neg_hi:[0,1]
	v_pk_add_f32 v[164:165], v[164:165], v[80:81] op_sel_hi:[1,0] neg_lo:[0,1] neg_hi:[0,1]
	v_pk_add_f32 v[148:149], v[148:149], v[80:81] op_sel_hi:[1,0] neg_lo:[0,1] neg_hi:[0,1]
	v_pk_add_f32 v[166:167], v[166:167], v[80:81] op_sel_hi:[1,0] neg_lo:[0,1] neg_hi:[0,1]
	v_pk_add_f32 v[150:151], v[150:151], v[80:81] op_sel_hi:[1,0] neg_lo:[0,1] neg_hi:[0,1]
	v_pk_add_f32 v[168:169], v[168:169], v[80:81] op_sel_hi:[1,0] neg_lo:[0,1] neg_hi:[0,1]
	v_pk_add_f32 v[152:153], v[152:153], v[80:81] op_sel_hi:[1,0] neg_lo:[0,1] neg_hi:[0,1]
	v_pk_add_f32 v[170:171], v[170:171], v[80:81] op_sel_hi:[1,0] neg_lo:[0,1] neg_hi:[0,1]
	v_pk_add_f32 v[154:155], v[154:155], v[80:81] op_sel_hi:[1,0] neg_lo:[0,1] neg_hi:[0,1]
	v_pk_add_f32 v[172:173], v[172:173], v[80:81] op_sel_hi:[1,0] neg_lo:[0,1] neg_hi:[0,1]
	v_pk_add_f32 v[156:157], v[156:157], v[80:81] op_sel_hi:[1,0] neg_lo:[0,1] neg_hi:[0,1]
	v_pk_add_f32 v[174:175], v[174:175], v[80:81] op_sel_hi:[1,0] neg_lo:[0,1] neg_hi:[0,1]
	v_pk_add_f32 v[158:159], v[158:159], v[80:81] op_sel_hi:[1,0] neg_lo:[0,1] neg_hi:[0,1]
	v_mul_f32_e32 v14, v14, v0
	v_mov_b32_e32 v113, v112
	v_mov_b32_e32 v114, v112
	v_mov_b32_e32 v115, v112
	v_mov_b32_e32 v116, v112
	v_mov_b32_e32 v117, v112
	v_mov_b32_e32 v118, v112
	v_mov_b32_e32 v119, v112
	v_mov_b32_e32 v120, v112
	v_mov_b32_e32 v121, v112
	v_mov_b32_e32 v122, v112
	v_mov_b32_e32 v123, v112
	v_mov_b32_e32 v124, v112
	v_mov_b32_e32 v125, v112
	v_mov_b32_e32 v126, v112
	v_mov_b32_e32 v127, v112
	v_mov_b32_e32 v96, v112
	v_mov_b32_e32 v97, v112
	v_mov_b32_e32 v98, v112
	v_mov_b32_e32 v99, v112
	v_mov_b32_e32 v100, v112
	v_mov_b32_e32 v101, v112
	v_mov_b32_e32 v102, v112
	v_mov_b32_e32 v103, v112
	v_mov_b32_e32 v104, v112
	v_mov_b32_e32 v105, v112
	v_mov_b32_e32 v106, v112
	v_mov_b32_e32 v107, v112
	v_mov_b32_e32 v108, v112
	v_mov_b32_e32 v109, v112
	v_mov_b32_e32 v110, v112
	v_mov_b32_e32 v111, v112
	s_branch .LBB0_587
